# FFN2 weight conversion: filler batches after out-proj dropped and the next phase converts all batches with a static per-workgroup schedule (no atomic pop, no workgroup barriers per batch)
# baseline (speedup 1.0000x reference)
; #define LAS __attribute__((address_space(3)))
; __device__ __forceinline__ void convert_ffn_dyn(const float* Wg, const float* Wu, const float* Wd, bf16_t* GU, bf16_t* DN, LAS unsigned char* lds, unsigned* ctr, int max_batches, int tid, int wave, int lane) {
;     constexpr int I1 = (DM / 64) * (FF / 32), NB = 3 * I1 / 8;
;     LAS int* MISC = (LAS int*)(lds + MISC_LDS); LAS float* scr = (LAS float*)(lds + wave * 16384);
;     for (int n = 0; n < max_batches; ++n) {
;         if (tid == 0) MISC[0] = (int)atomicAdd(ctr, 1u);
;         __syncthreads();
;         const int b = __builtin_amdgcn_readfirstlane(MISC[0]);
;         __syncthreads();
;         if (b >= NB) break;
;         const int it = b * 8 + wave;
; __global__ void __launch_bounds__(512, 2) fwd_kernel(Params p) {
;     ...
;             PH_BEGIN
;                 convert_ffn_dyn(p.in[21], p.in[22], p.in[23], (bf16_t*)(ws + OFF_GU2), (bf16_t*)(ws + OFF_DN2), lds, CTL + 8, 1 << 30, tid, wave, lane);
.LBB0_1604:
	s_cmp_lt_i32 s18, 13
	s_cselect_b64 s[0:1], -1, 0
	s_cmp_gt_i32 s19, 12
	s_cselect_b64 s[4:5], -1, 0
	s_and_b64 s[0:1], s[0:1], s[4:5]
	s_andn2_b64 vcc, exec, s[0:1]
	s_mov_b32 s10, 13
	s_cbranch_vccnz .LBB0_1690
	v_readlane_b32 s0, v252, 48
	v_readlane_b32 s40, v252, 32
	s_waitcnt vmcnt(0)
	v_mov_b32_e32 v1, 0
	v_lshl_add_u32 v4, s0, 6, v224
	v_readlane_b32 s54, v252, 46
	v_readfirstlane_b32 s0, v4
	s_ashr_i32 s11, s0, 6
	s_mov_b64 s[0:1], s[16:17]
	s_add_u32 s6, s0, 0x9d80020
	s_addc_u32 s7, s1, 0
	s_lshl_b32 s4, s11, 14
	v_and_b32_e32 v8, 31, v4
	s_add_i32 s4, s4, 0
	v_lshlrev_b32_e32 v0, 2, v8
	v_readlane_b32 s55, v252, 47
	v_bfe_u32 v10, v4, 5, 1
	v_add_u32_e32 v9, s4, v0
	v_lshl_add_u64 v[2:3], s[54:55], 0, v[0:1]
	s_movk_i32 s8, 0x84
	v_mov_b32_e32 v0, 0x630
	v_mad_u32_u24 v50, v10, s8, v0
	v_mov_b32_e32 v0, 0xc60
	v_mad_u32_u24 v51, v10, s8, v0
	v_lshlrev_b32_e32 v0, 3, v4
	v_and_b32_e32 v0, 56, v0
	v_mul_u32_u24_e32 v43, 0x84, v0
	v_lshlrev_b32_e32 v0, 1, v0
	v_mul_u32_u24_e32 v49, 0x84, v10
	v_bfe_u32 v42, v4, 3, 3
	v_lshl_add_u64 v[6:7], s[0:1], 0, v[0:1]
	s_mov_b64 s[8:9], 0x8700000
	v_and_b32_e32 v96, 63, v4
	v_cmp_eq_u32_e64 s[36:37], 0, v4
	v_lshl_add_u64 v[4:5], v[6:7], 0, s[8:9]
	v_lshlrev_b32_e32 v0, 2, v42
	s_mov_b64 s[8:9], 0x5b00000
	s_add_i32 s21, 0, 0x20000
	v_add_u32_e32 v49, v9, v49
	v_add_u32_e32 v50, v9, v50
	v_add_u32_e32 v51, v9, v51
	s_mov_b32 s5, 0
	v_or_b32_e32 v11, 2, v10
	v_or_b32_e32 v12, 4, v10
	v_or_b32_e32 v13, 6, v10
	v_or_b32_e32 v14, 8, v10
	v_or_b32_e32 v15, 10, v10
	v_or_b32_e32 v16, 12, v10
	v_or_b32_e32 v17, 14, v10
	v_or_b32_e32 v18, 16, v10
	v_or_b32_e32 v19, 18, v10
	v_or_b32_e32 v20, 20, v10
	v_or_b32_e32 v21, 22, v10
	v_or_b32_e32 v22, 24, v10
	v_or_b32_e32 v23, 26, v10
	v_or_b32_e32 v24, 28, v10
	v_or_b32_e32 v25, 30, v10
	v_or_b32_e32 v26, 32, v10
	v_or_b32_e32 v27, 34, v10
	v_or_b32_e32 v28, 36, v10
	v_or_b32_e32 v29, 38, v10
	v_or_b32_e32 v30, 40, v10
	v_or_b32_e32 v31, 42, v10
	v_or_b32_e32 v32, 44, v10
	v_or_b32_e32 v33, 46, v10
	v_or_b32_e32 v34, 48, v10
	v_or_b32_e32 v35, 50, v10
	v_or_b32_e32 v36, 52, v10
	v_or_b32_e32 v37, 54, v10
	v_or_b32_e32 v38, 56, v10
	v_or_b32_e32 v39, 58, v10
	v_or_b32_e32 v40, 60, v10
	v_or_b32_e32 v41, 62, v10
	v_add3_u32 v43, s4, v43, v0
	v_or_b32_e32 v44, 8, v42
	v_or_b32_e32 v45, 16, v42
	v_or_b32_e32 v46, 24, v42
	v_lshl_add_u64 v[6:7], v[6:7], 0, s[8:9]
	s_mov_b32 s20, 2.0
	v_mov_b32_e32 v47, 1
	v_mov_b32_e32 v48, s21
	s_movk_i32 s23, 0x7fff
	s_mov_b32 s24, 0xffff0000
	v_lshlrev_b32_e32 v0, 2, v8
	s_movk_i32 s25, 0x5800
	v_add_u32_e32 v52, 0x400, v49
	v_add_u32_e32 v53, 0x400, v50
	v_add_u32_e32 v54, 0x400, v51
	v_readlane_b32 s41, v252, 33
	v_readlane_b32 s42, v252, 34
	v_readlane_b32 s43, v252, 35
	v_readlane_b32 s44, v252, 36
	v_readlane_b32 s45, v252, 37
	v_readlane_b32 s46, v252, 38
	v_readlane_b32 s47, v252, 39
	v_readlane_b32 s48, v252, 40
	v_readlane_b32 s49, v252, 41
	v_readlane_b32 s50, v252, 42
	v_readlane_b32 s51, v252, 43
	v_readlane_b32 s52, v252, 44
	v_readlane_b32 s53, v252, 45
	s_mov_b32 s32, s2
	s_branch .LBB0_1608

; #define LAS __attribute__((address_space(3)))
; __device__ __forceinline__ void transpose_item(const float* W, int K, int N, bf16_t* WT, int drow0, int k0, int n0, LAS float* scr, int lane) {
; #pragma unroll
;     for (int i = 0; i < 32; ++i) { const int kk = 2 * i + (lane >> 5); scr[kk * 33 + (lane & 31)] = __builtin_nontemporal_load(&W[(size_t)(k0 + kk) * N + n0 + (lane & 31)]); }
; __device__ __forceinline__ void convert_ffn_dyn(const float* Wg, const float* Wu, const float* Wd, bf16_t* GU, bf16_t* DN, LAS unsigned char* lds, unsigned* ctr, int max_batches, int tid, int wave, int lane) {
;     ...
;     for (int n = 0; n < max_batches; ++n) {
;         if (tid == 0) MISC[0] = (int)atomicAdd(ctr, 1u);
;         __syncthreads();
;         const int b = __builtin_amdgcn_readfirstlane(MISC[0]);
;         __syncthreads();
;         if (b >= NB) break;
;         const int it = b * 8 + wave;
;         if (it < 2 * I1) { const int up = it >= I1, r = it - up * I1, kb = r / (FF / 32), nb = r % (FF / 32), n0 = nb * 32;
;             transpose_item(up ? Wu : Wg, DM, FF, GU, 256 * (n0 >> 7) + up * 128 + (n0 & 127), kb * 64, n0, scr, lane); }
;         else { const int r = it - 2 * I1, kb = r / (DM / 32), nb = r % (DM / 32); transpose_item(Wd, FF, DM, DN, nb * 32, kb * 64, nb * 32, scr, lane); }
.LBB0_1608:
	s_mov_b32 s4, s32
	s_add_i32 s32, s32, s22
	s_mov_b64 s[8:9], -1
	s_cmpk_gt_i32 s4, 0x83f
	s_cbranch_scc1 .LBB0_1607
	s_lshl_b32 s26, s4, 3
	s_add_i32 s26, s26, s11
	s_cmpk_gt_i32 s26, 0x2bff
	v_add_u32_e32 v57, 0x800, v51
	v_add_u32_e32 v56, 0xc00, v51
	v_add_u32_e32 v55, 0x1000, v51
	s_cbranch_scc0 .LBB0_1613
	s_and_b32 s4, s26, 0x7fffffc0
	s_add_i32 s8, s4, 0xffffd400
	s_lshl_b32 s4, s26, 5
	s_and_b32 s27, s4, 0x7e0
	s_lshl_b32 s4, s27, 2
	v_or_b32_e32 v58, s8, v10
	v_mov_b32_e32 v59, v1
	v_lshl_add_u64 v[8:9], v[2:3], 0, s[4:5]
	v_lshlrev_b64 v[58:59], 13, v[58:59]
	v_lshl_add_u64 v[58:59], v[8:9], 0, v[58:59]
	global_load_dword v60, v[58:59], off nt
	v_or_b32_e32 v58, s8, v11
	v_mov_b32_e32 v59, v1
	v_lshlrev_b64 v[58:59], 13, v[58:59]
	v_lshl_add_u64 v[58:59], v[8:9], 0, v[58:59]
	global_load_dword v58, v[58:59], off nt
	v_mov_b32_e32 v59, v1
	s_mov_b32 s9, s5
	s_waitcnt vmcnt(0)
	ds_write2_b32 v49, v60, v58 offset1:66
	v_or_b32_e32 v58, s8, v12
	v_lshlrev_b64 v[58:59], 13, v[58:59]
	v_lshl_add_u64 v[58:59], v[8:9], 0, v[58:59]
	global_load_dword v60, v[58:59], off nt
	v_or_b32_e32 v58, s8, v13
	v_mov_b32_e32 v59, v1
	v_lshlrev_b64 v[58:59], 13, v[58:59]
	v_lshl_add_u64 v[58:59], v[8:9], 0, v[58:59]
	global_load_dword v58, v[58:59], off nt
	v_mov_b32_e32 v59, v1
	s_waitcnt vmcnt(0)
	ds_write2_b32 v49, v60, v58 offset0:132 offset1:198
	v_or_b32_e32 v58, s8, v14
	v_lshlrev_b64 v[58:59], 13, v[58:59]
	v_lshl_add_u64 v[58:59], v[8:9], 0, v[58:59]
	global_load_dword v60, v[58:59], off nt
	v_or_b32_e32 v58, s8, v15
	v_mov_b32_e32 v59, v1
	v_lshlrev_b64 v[58:59], 13, v[58:59]
	v_lshl_add_u64 v[58:59], v[8:9], 0, v[58:59]
	global_load_dword v58, v[58:59], off nt
	v_mov_b32_e32 v59, v1
	s_waitcnt vmcnt(0)
	ds_write2_b32 v52, v60, v58 offset0:8 offset1:74
	v_or_b32_e32 v58, s8, v16
	v_lshlrev_b64 v[58:59], 13, v[58:59]
	v_lshl_add_u64 v[58:59], v[8:9], 0, v[58:59]
	global_load_dword v60, v[58:59], off nt
	v_or_b32_e32 v58, s8, v17
	v_mov_b32_e32 v59, v1
	v_lshlrev_b64 v[58:59], 13, v[58:59]
	v_lshl_add_u64 v[58:59], v[8:9], 0, v[58:59]
	global_load_dword v58, v[58:59], off nt
	v_mov_b32_e32 v59, v1
	s_waitcnt vmcnt(0)
	ds_write2_b32 v50, v60, v58 offset1:66
	v_or_b32_e32 v58, s8, v18
	v_lshlrev_b64 v[58:59], 13, v[58:59]
	v_lshl_add_u64 v[58:59], v[8:9], 0, v[58:59]
	global_load_dword v60, v[58:59], off nt
	v_or_b32_e32 v58, s8, v19
	v_mov_b32_e32 v59, v1
	v_lshlrev_b64 v[58:59], 13, v[58:59]
	v_lshl_add_u64 v[58:59], v[8:9], 0, v[58:59]
	global_load_dword v58, v[58:59], off nt
	v_mov_b32_e32 v59, v1
	s_waitcnt vmcnt(0)
	ds_write2_b32 v50, v60, v58 offset0:132 offset1:198
	v_or_b32_e32 v58, s8, v20
	v_lshlrev_b64 v[58:59], 13, v[58:59]
	v_lshl_add_u64 v[58:59], v[8:9], 0, v[58:59]
	global_load_dword v60, v[58:59], off nt
	v_or_b32_e32 v58, s8, v21
	v_mov_b32_e32 v59, v1
	v_lshlrev_b64 v[58:59], 13, v[58:59]
	v_lshl_add_u64 v[58:59], v[8:9], 0, v[58:59]
	global_load_dword v58, v[58:59], off nt
	v_mov_b32_e32 v59, v1
	s_waitcnt vmcnt(0)
	ds_write2_b32 v53, v60, v58 offset0:8 offset1:74
	v_or_b32_e32 v58, s8, v22
	v_lshlrev_b64 v[58:59], 13, v[58:59]
	v_lshl_add_u64 v[58:59], v[8:9], 0, v[58:59]
	global_load_dword v60, v[58:59], off nt
	v_or_b32_e32 v58, s8, v23
	v_mov_b32_e32 v59, v1
	v_lshlrev_b64 v[58:59], 13, v[58:59]
	v_lshl_add_u64 v[58:59], v[8:9], 0, v[58:59]
	global_load_dword v58, v[58:59], off nt
	v_mov_b32_e32 v59, v1
	s_waitcnt vmcnt(0)
	ds_write2_b32 v51, v60, v58 offset1:66
	v_or_b32_e32 v58, s8, v24
	v_lshlrev_b64 v[58:59], 13, v[58:59]
	v_lshl_add_u64 v[58:59], v[8:9], 0, v[58:59]
	global_load_dword v60, v[58:59], off nt
	v_or_b32_e32 v58, s8, v25
	v_mov_b32_e32 v59, v1
	v_lshlrev_b64 v[58:59], 13, v[58:59]
	v_lshl_add_u64 v[58:59], v[8:9], 0, v[58:59]
	global_load_dword v58, v[58:59], off nt
	v_mov_b32_e32 v59, v1
	s_waitcnt vmcnt(0)
	ds_write2_b32 v51, v60, v58 offset0:132 offset1:198
	v_or_b32_e32 v58, s8, v26
	v_lshlrev_b64 v[58:59], 13, v[58:59]
	v_lshl_add_u64 v[58:59], v[8:9], 0, v[58:59]
	global_load_dword v60, v[58:59], off nt
	v_or_b32_e32 v58, s8, v27
	v_mov_b32_e32 v59, v1
	v_lshlrev_b64 v[58:59], 13, v[58:59]
	v_lshl_add_u64 v[58:59], v[8:9], 0, v[58:59]
	global_load_dword v58, v[58:59], off nt
	v_mov_b32_e32 v59, v1
	s_waitcnt vmcnt(0)
	ds_write2_b32 v54, v60, v58 offset0:8 offset1:74
	v_or_b32_e32 v58, s8, v28
	v_lshlrev_b64 v[58:59], 13, v[58:59]
	v_lshl_add_u64 v[58:59], v[8:9], 0, v[58:59]
	global_load_dword v60, v[58:59], off nt
	v_or_b32_e32 v58, s8, v29
	v_mov_b32_e32 v59, v1
	v_lshlrev_b64 v[58:59], 13, v[58:59]
	v_lshl_add_u64 v[58:59], v[8:9], 0, v[58:59]
	global_load_dword v58, v[58:59], off nt
	v_mov_b32_e32 v59, v1
	s_waitcnt vmcnt(0)
	ds_write2_b32 v54, v60, v58 offset0:140 offset1:206
	v_or_b32_e32 v58, s8, v30
	v_lshlrev_b64 v[58:59], 13, v[58:59]
	v_lshl_add_u64 v[58:59], v[8:9], 0, v[58:59]
	global_load_dword v60, v[58:59], off nt
	v_or_b32_e32 v58, s8, v31
	v_mov_b32_e32 v59, v1
	v_lshlrev_b64 v[58:59], 13, v[58:59]
	v_lshl_add_u64 v[58:59], v[8:9], 0, v[58:59]
	global_load_dword v58, v[58:59], off nt
	v_mov_b32_e32 v59, v1
	s_waitcnt vmcnt(0)
	ds_write2_b32 v57, v60, v58 offset0:16 offset1:82
	v_or_b32_e32 v58, s8, v32
	v_lshlrev_b64 v[58:59], 13, v[58:59]
	v_lshl_add_u64 v[58:59], v[8:9], 0, v[58:59]
	global_load_dword v60, v[58:59], off nt
	v_or_b32_e32 v58, s8, v33
	v_mov_b32_e32 v59, v1
	v_lshlrev_b64 v[58:59], 13, v[58:59]
	v_lshl_add_u64 v[58:59], v[8:9], 0, v[58:59]
	global_load_dword v58, v[58:59], off nt
	v_mov_b32_e32 v59, v1
	s_waitcnt vmcnt(0)
; #define LAS __attribute__((address_space(3)))
; __device__ __forceinline__ unsigned pk2(float lo, float hi) { return f2bf(lo) | (f2bf(hi) << 16); }
; #define LDS_WAIT() asm volatile("s_waitcnt lgkmcnt(0)" ::: "memory")
; __device__ __forceinline__ void transpose_item(const float* W, int K, int N, bf16_t* WT, int drow0, int k0, int n0, LAS float* scr, int lane) {
;     ...
;     for (int i = 0; i < 32; ++i) { const int kk = 2 * i + (lane >> 5); scr[kk * 33 + (lane & 31)] = __builtin_nontemporal_load(&W[(size_t)(k0 + kk) * N + n0 + (lane & 31)]); }
;     LDS_WAIT();
;     const int c = lane & 7;
; #pragma unroll
;     for (int j = 0; j < 4; ++j) { const int n = (lane >> 3) + 8 * j; const LAS float* s = scr + (8 * c) * 33 + n;
;         u32x4 o; o.x = pk2(s[0 * 33], s[1 * 33]); o.y = pk2(s[2 * 33], s[3 * 33]); o.z = pk2(s[4 * 33], s[5 * 33]); o.w = pk2(s[6 * 33], s[7 * 33]);
;         *(u32x4*)(WT + (size_t)(drow0 + n) * K + k0 + 8 * c) = o; }
	ds_write2_b32 v57, v60, v58 offset0:148 offset1:214
	v_or_b32_e32 v58, s8, v34
	v_lshlrev_b64 v[58:59], 13, v[58:59]
	v_lshl_add_u64 v[58:59], v[8:9], 0, v[58:59]
	global_load_dword v60, v[58:59], off nt
	v_or_b32_e32 v58, s8, v35
	v_mov_b32_e32 v59, v1
	v_lshlrev_b64 v[58:59], 13, v[58:59]
	v_lshl_add_u64 v[58:59], v[8:9], 0, v[58:59]
	global_load_dword v58, v[58:59], off nt
	v_mov_b32_e32 v59, v1
	s_waitcnt vmcnt(0)
	ds_write2_b32 v56, v60, v58 offset0:24 offset1:90
	v_or_b32_e32 v58, s8, v36
	v_lshlrev_b64 v[58:59], 13, v[58:59]
	v_lshl_add_u64 v[58:59], v[8:9], 0, v[58:59]
	global_load_dword v60, v[58:59], off nt
	v_or_b32_e32 v58, s8, v37
	v_mov_b32_e32 v59, v1
	v_lshlrev_b64 v[58:59], 13, v[58:59]
	v_lshl_add_u64 v[58:59], v[8:9], 0, v[58:59]
	global_load_dword v58, v[58:59], off nt
	v_mov_b32_e32 v59, v1
	s_waitcnt vmcnt(0)
	ds_write2_b32 v56, v60, v58 offset0:156 offset1:222
	v_or_b32_e32 v58, s8, v38
	v_lshlrev_b64 v[58:59], 13, v[58:59]
	v_lshl_add_u64 v[58:59], v[8:9], 0, v[58:59]
	global_load_dword v60, v[58:59], off nt
	v_or_b32_e32 v58, s8, v39
	v_mov_b32_e32 v59, v1
	v_lshlrev_b64 v[58:59], 13, v[58:59]
	v_lshl_add_u64 v[58:59], v[8:9], 0, v[58:59]
	global_load_dword v58, v[58:59], off nt
	v_mov_b32_e32 v59, v1
	s_waitcnt vmcnt(0)
	ds_write2_b32 v55, v60, v58 offset0:32 offset1:98
	v_or_b32_e32 v58, s8, v40
	v_lshlrev_b64 v[58:59], 13, v[58:59]
	v_lshl_add_u64 v[58:59], v[8:9], 0, v[58:59]
	global_load_dword v60, v[58:59], off nt
	v_or_b32_e32 v58, s8, v41
	v_mov_b32_e32 v59, v1
	v_lshlrev_b64 v[58:59], 13, v[58:59]
	v_lshl_add_u64 v[8:9], v[8:9], 0, v[58:59]
	global_load_dword v8, v[8:9], off nt
	s_waitcnt vmcnt(0)
	ds_write2_b32 v55, v60, v8 offset0:164 offset1:230
	s_waitcnt lgkmcnt(0)
	ds_read_b32 v58, v43
	ds_read_b32 v59, v43 offset:132
	v_lshl_add_u64 v[8:9], s[8:9], 1, v[4:5]
	s_mov_b64 s[8:9], 0
	s_waitcnt lgkmcnt(1)
	v_bfe_u32 v60, v58, 16, 1
	v_add3_u32 v58, v58, v60, s23
	s_waitcnt lgkmcnt(0)
	v_bfe_u32 v60, v59, 16, 1
	v_lshrrev_b32_e32 v58, 16, v58
	v_add3_u32 v59, v59, v60, s23
	v_and_or_b32 v58, v59, s24, v58
	ds_read_b32 v59, v43 offset:264
	ds_read_b32 v60, v43 offset:396
	s_waitcnt lgkmcnt(1)
	v_bfe_u32 v61, v59, 16, 1
	v_add3_u32 v59, v59, v61, s23
	s_waitcnt lgkmcnt(0)
	v_bfe_u32 v61, v60, 16, 1
	v_lshrrev_b32_e32 v59, 16, v59
	v_add3_u32 v60, v60, v61, s23
	v_and_or_b32 v59, v60, s24, v59
	ds_read_b32 v60, v43 offset:528
	ds_read_b32 v61, v43 offset:660
	s_waitcnt lgkmcnt(1)
	v_bfe_u32 v62, v60, 16, 1
	v_add3_u32 v60, v60, v62, s23
	s_waitcnt lgkmcnt(0)
	v_bfe_u32 v62, v61, 16, 1
	v_lshrrev_b32_e32 v60, 16, v60
	v_add3_u32 v61, v61, v62, s23
	v_and_or_b32 v60, v61, s24, v60
	ds_read_b32 v61, v43 offset:792
	ds_read_b32 v62, v43 offset:924
	s_waitcnt lgkmcnt(1)
	v_bfe_u32 v63, v61, 16, 1
	v_add3_u32 v61, v61, v63, s23
	s_waitcnt lgkmcnt(0)
	v_bfe_u32 v63, v62, 16, 1
	v_lshrrev_b32_e32 v61, 16, v61
	v_add3_u32 v62, v62, v63, s23
	v_and_or_b32 v61, v62, s24, v61
	v_or_b32_e32 v62, s27, v42
	v_mul_u32_u24_e32 v62, 0x1600, v62
	v_lshlrev_b32_e32 v62, 1, v62
	v_mov_b32_e32 v63, v1
	v_lshl_add_u64 v[62:63], v[8:9], 0, v[62:63]
	flat_store_dwordx4 v[62:63], v[58:61]
	ds_read_b32 v58, v43 offset:32
	ds_read_b32 v59, v43 offset:164
	s_waitcnt lgkmcnt(0)
	v_bfe_u32 v60, v58, 16, 1
	v_add3_u32 v58, v58, v60, s23
	v_bfe_u32 v60, v59, 16, 1
	v_lshrrev_b32_e32 v58, 16, v58
	v_add3_u32 v59, v59, v60, s23
	v_and_or_b32 v58, v59, s24, v58
	ds_read_b32 v59, v43 offset:296
	ds_read_b32 v60, v43 offset:428
	s_waitcnt lgkmcnt(0)
	v_bfe_u32 v61, v59, 16, 1
	v_add3_u32 v59, v59, v61, s23
	v_bfe_u32 v61, v60, 16, 1
	v_lshrrev_b32_e32 v59, 16, v59
	v_add3_u32 v60, v60, v61, s23
	v_and_or_b32 v59, v60, s24, v59
	ds_read_b32 v60, v43 offset:560
	ds_read_b32 v61, v43 offset:692
	s_waitcnt lgkmcnt(0)
	v_bfe_u32 v62, v60, 16, 1
	v_add3_u32 v60, v60, v62, s23
	v_bfe_u32 v62, v61, 16, 1
	v_lshrrev_b32_e32 v60, 16, v60
	v_add3_u32 v61, v61, v62, s23
	v_and_or_b32 v60, v61, s24, v60
	ds_read_b32 v61, v43 offset:824
	ds_read_b32 v62, v43 offset:956
	s_waitcnt lgkmcnt(0)
	v_bfe_u32 v63, v61, 16, 1
	v_add3_u32 v61, v61, v63, s23
	v_bfe_u32 v63, v62, 16, 1
	v_lshrrev_b32_e32 v61, 16, v61
	v_add3_u32 v62, v62, v63, s23
	v_and_or_b32 v61, v62, s24, v61
	v_or_b32_e32 v62, s27, v44
	v_mul_u32_u24_e32 v62, 0x1600, v62
	v_lshlrev_b32_e32 v62, 1, v62
	v_mov_b32_e32 v63, v1
	v_lshl_add_u64 v[62:63], v[8:9], 0, v[62:63]
	flat_store_dwordx4 v[62:63], v[58:61]
	ds_read_b32 v58, v43 offset:64
	ds_read_b32 v59, v43 offset:196
	s_waitcnt lgkmcnt(0)
	v_bfe_u32 v60, v58, 16, 1
	v_add3_u32 v58, v58, v60, s23
	v_bfe_u32 v60, v59, 16, 1
	v_lshrrev_b32_e32 v58, 16, v58
	v_add3_u32 v59, v59, v60, s23
	v_and_or_b32 v58, v59, s24, v58
	ds_read_b32 v59, v43 offset:328
	ds_read_b32 v60, v43 offset:460
	s_waitcnt lgkmcnt(0)
	v_bfe_u32 v61, v59, 16, 1
	v_add3_u32 v59, v59, v61, s23
	v_bfe_u32 v61, v60, 16, 1
	v_lshrrev_b32_e32 v59, 16, v59
	v_add3_u32 v60, v60, v61, s23
	v_and_or_b32 v59, v60, s24, v59
	ds_read_b32 v60, v43 offset:592
	ds_read_b32 v61, v43 offset:724
	s_waitcnt lgkmcnt(0)
	v_bfe_u32 v62, v60, 16, 1
	v_add3_u32 v60, v60, v62, s23
	v_bfe_u32 v62, v61, 16, 1
	v_lshrrev_b32_e32 v60, 16, v60
	v_add3_u32 v61, v61, v62, s23
	v_and_or_b32 v60, v61, s24, v60
	ds_read_b32 v61, v43 offset:856
	ds_read_b32 v62, v43 offset:988
	s_waitcnt lgkmcnt(0)
	v_bfe_u32 v63, v61, 16, 1
	v_add3_u32 v61, v61, v63, s23
	v_bfe_u32 v63, v62, 16, 1
	v_lshrrev_b32_e32 v61, 16, v61
	v_add3_u32 v62, v62, v63, s23
	v_and_or_b32 v61, v62, s24, v61
	v_or_b32_e32 v62, s27, v45
	v_mul_u32_u24_e32 v62, 0x1600, v62
	v_lshlrev_b32_e32 v62, 1, v62
	v_mov_b32_e32 v63, v1
	v_lshl_add_u64 v[62:63], v[8:9], 0, v[62:63]
	flat_store_dwordx4 v[62:63], v[58:61]
	ds_read_b32 v58, v43 offset:96
	ds_read_b32 v59, v43 offset:228
	s_waitcnt lgkmcnt(0)
	v_bfe_u32 v60, v58, 16, 1
	v_add3_u32 v58, v58, v60, s23
	v_bfe_u32 v60, v59, 16, 1
	v_lshrrev_b32_e32 v58, 16, v58
	v_add3_u32 v59, v59, v60, s23
	v_and_or_b32 v58, v59, s24, v58
	ds_read_b32 v59, v43 offset:360
	ds_read_b32 v60, v43 offset:492
	s_waitcnt lgkmcnt(0)
	v_bfe_u32 v61, v59, 16, 1
	v_add3_u32 v59, v59, v61, s23
	v_bfe_u32 v61, v60, 16, 1
	v_lshrrev_b32_e32 v59, 16, v59
	v_add3_u32 v60, v60, v61, s23
	v_and_or_b32 v59, v60, s24, v59
	ds_read_b32 v60, v43 offset:624
	ds_read_b32 v61, v43 offset:756
	s_waitcnt lgkmcnt(0)
	v_bfe_u32 v62, v60, 16, 1
	v_add3_u32 v60, v60, v62, s23
	v_bfe_u32 v62, v61, 16, 1
	v_lshrrev_b32_e32 v60, 16, v60
	v_add3_u32 v61, v61, v62, s23
	v_and_or_b32 v60, v61, s24, v60
	ds_read_b32 v61, v43 offset:888
	ds_read_b32 v62, v43 offset:1020
	s_waitcnt lgkmcnt(0)
	v_bfe_u32 v63, v61, 16, 1
	v_add3_u32 v61, v61, v63, s23
	v_bfe_u32 v63, v62, 16, 1
	v_lshrrev_b32_e32 v61, 16, v61
	v_add3_u32 v62, v62, v63, s23
	v_and_or_b32 v61, v62, s24, v61
	v_or_b32_e32 v62, s27, v46
	v_mul_u32_u24_e32 v62, 0x1600, v62
	v_lshlrev_b32_e32 v62, 1, v62
	v_mov_b32_e32 v63, v1
	v_lshl_add_u64 v[8:9], v[8:9], 0, v[62:63]
	flat_store_dwordx4 v[8:9], v[58:61]
	s_waitcnt lgkmcnt(0)
